# K norms folded into the proj1 epilogue (L2-hot re-read of the two K tiles each WG owns) instead of a FoX-phase pre-pass; Cauchy-Schwarz early exit kept
# speedup vs baseline: 1.0037x; 1.0019x over previous
.LBB0_564:
	v_lshl_add_u32 v150, s4, 8, v152
	v_ashrrev_i32_e32 v151, 31, v150
	v_lshl_add_u64 v[144:145], v[150:151], 2, s[16:17]
	s_nop 0
	v_lshl_or_b32 v146, s5, 8, v154
	s_cmp_lt_i32 s5, 8
	v_ashrrev_i32_e32 v147, 31, v146
	s_cselect_b64 vcc, -1, 0
	v_lshlrev_b64 v[148:149], 1, v[146:147]
	v_cndmask_b32_e32 v161, 1.0, v160, vcc
	v_lshlrev_b64 v[164:165], 14, v[150:151]
	v_or_b32_e32 v162, 16, v150
	s_nop 0
	v_fmamk_f32 v146, v242, 0x3a000000, v158
	v_rsq_f32_e32 v252, v146
	s_nop 0
	v_mul_f32_e32 v252, v252, v161
	v_ashrrev_i32_e32 v163, 31, v162
	v_lshl_add_u64 v[146:147], s[10:11], 0, v[164:165]
	v_lshl_add_u64 v[146:147], v[146:147], 0, v[148:149]
	v_lshl_add_u64 v[164:165], v[162:163], 2, s[16:17]
	v_pk_mul_f32 v[126:127], v[126:127], v[252:253] op_sel_hi:[1,0]
	v_pk_mul_f32 v[124:125], v[124:125], v[252:253] op_sel_hi:[1,0]
	v_pk_mul_f32 v[122:123], v[122:123], v[252:253] op_sel_hi:[1,0]
	v_pk_mul_f32 v[120:121], v[120:121], v[252:253] op_sel_hi:[1,0]
	v_pk_mul_f32 v[118:119], v[118:119], v[252:253] op_sel_hi:[1,0]
	v_pk_mul_f32 v[116:117], v[116:117], v[252:253] op_sel_hi:[1,0]
	v_pk_mul_f32 v[168:169], v[114:115], v[252:253] op_sel_hi:[1,0]
	v_pk_mul_f32 v[166:167], v[112:113], v[252:253] op_sel_hi:[1,0]
	v_cvt_pk_bf16_f32 v112, v124, v125
	v_cvt_pk_bf16_f32 v113, v126, v127
	v_cvt_pk_bf16_f32 v114, v120, v121
	v_cvt_pk_bf16_f32 v115, v122, v123
	v_cvt_pk_bf16_f32 v116, v116, v117
	v_cvt_pk_bf16_f32 v117, v118, v119
	v_cvt_pk_bf16_f32 v118, v166, v167
	v_cvt_pk_bf16_f32 v119, v168, v169
	global_store_dwordx4 v[146:147], v[112:115], off
	global_store_dwordx4 v[146:147], v[116:119], off offset:256
	s_nop 0
	v_or_b32_e32 v112, 32, v150
	v_ashrrev_i32_e32 v113, 31, v112
	v_lshl_add_u64 v[116:117], v[112:113], 2, s[16:17]
	s_nop 0
	v_fmamk_f32 v114, v243, 0x3a000000, v158
	v_rsq_f32_e32 v252, v114
	s_nop 0
	v_mul_f32_e32 v252, v252, v161
	v_lshlrev_b64 v[114:115], 14, v[162:163]
	v_lshl_add_u64 v[114:115], s[10:11], 0, v[114:115]
	v_lshl_add_u64 v[114:115], v[114:115], 0, v[148:149]
	v_pk_mul_f32 v[110:111], v[110:111], v[252:253] op_sel_hi:[1,0]
	v_pk_mul_f32 v[108:109], v[108:109], v[252:253] op_sel_hi:[1,0]
	v_pk_mul_f32 v[106:107], v[106:107], v[252:253] op_sel_hi:[1,0]
	v_pk_mul_f32 v[104:105], v[104:105], v[252:253] op_sel_hi:[1,0]
	v_pk_mul_f32 v[102:103], v[102:103], v[252:253] op_sel_hi:[1,0]
	v_pk_mul_f32 v[100:101], v[100:101], v[252:253] op_sel_hi:[1,0]
	v_pk_mul_f32 v[120:121], v[98:99], v[252:253] op_sel_hi:[1,0]
	v_pk_mul_f32 v[118:119], v[96:97], v[252:253] op_sel_hi:[1,0]
	v_cvt_pk_bf16_f32 v96, v108, v109
	v_cvt_pk_bf16_f32 v97, v110, v111
	v_cvt_pk_bf16_f32 v98, v104, v105
	v_cvt_pk_bf16_f32 v99, v106, v107
	v_cvt_pk_bf16_f32 v100, v100, v101
	v_cvt_pk_bf16_f32 v101, v102, v103
	v_cvt_pk_bf16_f32 v102, v118, v119
	v_cvt_pk_bf16_f32 v103, v120, v121
	global_store_dwordx4 v[114:115], v[96:99], off
	global_store_dwordx4 v[114:115], v[100:103], off offset:256
	s_nop 0
	v_or_b32_e32 v96, 48, v150
	v_ashrrev_i32_e32 v97, 31, v96
	v_lshl_add_u64 v[100:101], v[96:97], 2, s[16:17]
	s_nop 0
	v_fmamk_f32 v98, v244, 0x3a000000, v158
	v_rsq_f32_e32 v252, v98
	s_nop 0
	v_mul_f32_e32 v252, v252, v161
	v_lshlrev_b64 v[98:99], 14, v[112:113]
	v_lshl_add_u64 v[98:99], s[10:11], 0, v[98:99]
	v_lshl_add_u64 v[98:99], v[98:99], 0, v[148:149]
	v_pk_mul_f32 v[94:95], v[94:95], v[252:253] op_sel_hi:[1,0]
	v_pk_mul_f32 v[92:93], v[92:93], v[252:253] op_sel_hi:[1,0]
	v_pk_mul_f32 v[90:91], v[90:91], v[252:253] op_sel_hi:[1,0]
	v_pk_mul_f32 v[88:89], v[88:89], v[252:253] op_sel_hi:[1,0]
	v_pk_mul_f32 v[86:87], v[86:87], v[252:253] op_sel_hi:[1,0]
	v_pk_mul_f32 v[84:85], v[84:85], v[252:253] op_sel_hi:[1,0]
	v_pk_mul_f32 v[104:105], v[82:83], v[252:253] op_sel_hi:[1,0]
	v_pk_mul_f32 v[102:103], v[80:81], v[252:253] op_sel_hi:[1,0]
	v_cvt_pk_bf16_f32 v80, v92, v93
	v_cvt_pk_bf16_f32 v81, v94, v95
	v_cvt_pk_bf16_f32 v82, v88, v89
	v_cvt_pk_bf16_f32 v83, v90, v91
	v_cvt_pk_bf16_f32 v84, v84, v85
	v_cvt_pk_bf16_f32 v85, v86, v87
	v_cvt_pk_bf16_f32 v86, v102, v103
	v_cvt_pk_bf16_f32 v87, v104, v105
	global_store_dwordx4 v[98:99], v[80:83], off
	global_store_dwordx4 v[98:99], v[84:87], off offset:256
	s_nop 0
	s_nop 0
	v_fmamk_f32 v80, v245, 0x3a000000, v158
	v_rsq_f32_e32 v252, v80
	s_nop 0
	v_mul_f32_e32 v252, v252, v161
	v_lshlrev_b64 v[80:81], 14, v[96:97]
	v_lshl_add_u64 v[80:81], s[10:11], 0, v[80:81]
	v_lshl_add_u64 v[80:81], v[80:81], 0, v[148:149]
	v_pk_mul_f32 v[78:79], v[78:79], v[252:253] op_sel_hi:[1,0]
	v_pk_mul_f32 v[76:77], v[76:77], v[252:253] op_sel_hi:[1,0]
	v_pk_mul_f32 v[74:75], v[74:75], v[252:253] op_sel_hi:[1,0]
	v_pk_mul_f32 v[72:73], v[72:73], v[252:253] op_sel_hi:[1,0]
	v_pk_mul_f32 v[70:71], v[70:71], v[252:253] op_sel_hi:[1,0]
	v_pk_mul_f32 v[68:69], v[68:69], v[252:253] op_sel_hi:[1,0]
	v_pk_mul_f32 v[84:85], v[66:67], v[252:253] op_sel_hi:[1,0]
	v_pk_mul_f32 v[82:83], v[64:65], v[252:253] op_sel_hi:[1,0]
	v_cvt_pk_bf16_f32 v64, v76, v77
	v_cvt_pk_bf16_f32 v65, v78, v79
	v_cvt_pk_bf16_f32 v66, v72, v73
	v_cvt_pk_bf16_f32 v67, v74, v75
	v_cvt_pk_bf16_f32 v68, v68, v69
	v_cvt_pk_bf16_f32 v69, v70, v71
	v_cvt_pk_bf16_f32 v70, v82, v83
	v_cvt_pk_bf16_f32 v71, v84, v85
	global_store_dwordx4 v[80:81], v[64:67], off
	global_store_dwordx4 v[80:81], v[68:71], off offset:256
	s_nop 0
	s_nop 0
	v_fmamk_f32 v64, v246, 0x3a000000, v158
	v_rsq_f32_e32 v252, v64
	s_nop 0
	v_mul_f32_e32 v252, v252, v161
	v_lshl_add_u64 v[64:65], v[146:147], 0, s[20:21]
	v_add_co_u32_e32 v66, vcc, s75, v146
	v_addc_co_u32_e32 v67, vcc, 0, v147, vcc
	v_pk_mul_f32 v[62:63], v[62:63], v[252:253] op_sel_hi:[1,0]
	v_pk_mul_f32 v[60:61], v[60:61], v[252:253] op_sel_hi:[1,0]
	v_pk_mul_f32 v[58:59], v[58:59], v[252:253] op_sel_hi:[1,0]
	v_pk_mul_f32 v[56:57], v[56:57], v[252:253] op_sel_hi:[1,0]
	v_pk_mul_f32 v[54:55], v[54:55], v[252:253] op_sel_hi:[1,0]
	v_pk_mul_f32 v[52:53], v[52:53], v[252:253] op_sel_hi:[1,0]
	v_pk_mul_f32 v[70:71], v[50:51], v[252:253] op_sel_hi:[1,0]
	v_pk_mul_f32 v[68:69], v[48:49], v[252:253] op_sel_hi:[1,0]
	v_cvt_pk_bf16_f32 v48, v60, v61
	v_cvt_pk_bf16_f32 v49, v62, v63
	v_cvt_pk_bf16_f32 v50, v56, v57
	v_cvt_pk_bf16_f32 v51, v58, v59
	v_cvt_pk_bf16_f32 v52, v52, v53
	v_cvt_pk_bf16_f32 v53, v54, v55
	v_cvt_pk_bf16_f32 v54, v68, v69
	v_cvt_pk_bf16_f32 v55, v70, v71
	global_store_dwordx4 v[66:67], v[48:51], off
	global_store_dwordx4 v[64:65], v[52:55], off offset:256
	s_nop 0
	s_nop 0
	v_fmamk_f32 v48, v247, 0x3a000000, v158
	v_rsq_f32_e32 v252, v48
	s_nop 0
	v_mul_f32_e32 v252, v252, v161
	v_lshl_add_u64 v[48:49], v[146:147], 0, s[22:23]
	v_add_co_u32_e32 v50, vcc, s76, v146
	v_addc_co_u32_e32 v51, vcc, 0, v147, vcc
	v_pk_mul_f32 v[46:47], v[46:47], v[252:253] op_sel_hi:[1,0]
	v_pk_mul_f32 v[44:45], v[44:45], v[252:253] op_sel_hi:[1,0]
	v_pk_mul_f32 v[42:43], v[42:43], v[252:253] op_sel_hi:[1,0]
	v_pk_mul_f32 v[40:41], v[40:41], v[252:253] op_sel_hi:[1,0]
	v_pk_mul_f32 v[38:39], v[38:39], v[252:253] op_sel_hi:[1,0]
	v_pk_mul_f32 v[36:37], v[36:37], v[252:253] op_sel_hi:[1,0]
	v_pk_mul_f32 v[54:55], v[34:35], v[252:253] op_sel_hi:[1,0]
	v_pk_mul_f32 v[52:53], v[32:33], v[252:253] op_sel_hi:[1,0]
	v_cvt_pk_bf16_f32 v32, v44, v45
	v_cvt_pk_bf16_f32 v33, v46, v47
	v_cvt_pk_bf16_f32 v34, v40, v41
	v_cvt_pk_bf16_f32 v35, v42, v43
	v_cvt_pk_bf16_f32 v36, v36, v37
	v_cvt_pk_bf16_f32 v37, v38, v39
	v_cvt_pk_bf16_f32 v38, v52, v53
	v_cvt_pk_bf16_f32 v39, v54, v55
	global_store_dwordx4 v[50:51], v[32:35], off
	global_store_dwordx4 v[48:49], v[36:39], off offset:256
	s_nop 0
	s_nop 0
	v_fmamk_f32 v32, v248, 0x3a000000, v158
	v_rsq_f32_e32 v252, v32
	s_nop 0
	v_mul_f32_e32 v252, v252, v161
	v_lshl_add_u64 v[32:33], v[146:147], 0, s[24:25]
	v_add_co_u32_e32 v34, vcc, s77, v146
	v_addc_co_u32_e32 v35, vcc, 0, v147, vcc
	v_pk_mul_f32 v[30:31], v[30:31], v[252:253] op_sel_hi:[1,0]
	v_pk_mul_f32 v[28:29], v[28:29], v[252:253] op_sel_hi:[1,0]
	v_pk_mul_f32 v[26:27], v[26:27], v[252:253] op_sel_hi:[1,0]
	v_pk_mul_f32 v[24:25], v[24:25], v[252:253] op_sel_hi:[1,0]
	v_pk_mul_f32 v[22:23], v[22:23], v[252:253] op_sel_hi:[1,0]
	v_pk_mul_f32 v[20:21], v[20:21], v[252:253] op_sel_hi:[1,0]
	v_pk_mul_f32 v[38:39], v[18:19], v[252:253] op_sel_hi:[1,0]
	v_pk_mul_f32 v[36:37], v[16:17], v[252:253] op_sel_hi:[1,0]
	v_cvt_pk_bf16_f32 v16, v28, v29
	v_cvt_pk_bf16_f32 v17, v30, v31
	v_cvt_pk_bf16_f32 v18, v24, v25
	v_cvt_pk_bf16_f32 v19, v26, v27
	v_cvt_pk_bf16_f32 v20, v20, v21
	v_cvt_pk_bf16_f32 v21, v22, v23
	v_cvt_pk_bf16_f32 v22, v36, v37
	v_cvt_pk_bf16_f32 v23, v38, v39
	global_store_dwordx4 v[34:35], v[16:19], off
	global_store_dwordx4 v[32:33], v[20:23], off offset:256
	s_nop 0
	s_nop 0
	v_fmamk_f32 v16, v249, 0x3a000000, v158
	v_rsq_f32_e32 v252, v16
	s_nop 0
	v_mul_f32_e32 v252, v252, v161
	v_lshl_add_u64 v[16:17], v[146:147], 0, s[26:27]
	v_add_co_u32_e32 v18, vcc, s78, v146
	v_addc_co_u32_e32 v19, vcc, 0, v147, vcc
	v_pk_mul_f32 v[14:15], v[14:15], v[252:253] op_sel_hi:[1,0]
	v_pk_mul_f32 v[12:13], v[12:13], v[252:253] op_sel_hi:[1,0]
	v_pk_mul_f32 v[10:11], v[10:11], v[252:253] op_sel_hi:[1,0]
	v_pk_mul_f32 v[8:9], v[8:9], v[252:253] op_sel_hi:[1,0]
	s_andn2_b64 vcc, exec, s[0:1]
	v_pk_mul_f32 v[6:7], v[6:7], v[252:253] op_sel_hi:[1,0]
	v_pk_mul_f32 v[4:5], v[4:5], v[252:253] op_sel_hi:[1,0]
	v_pk_mul_f32 v[22:23], v[2:3], v[252:253] op_sel_hi:[1,0]
	v_pk_mul_f32 v[20:21], v[0:1], v[252:253] op_sel_hi:[1,0]
	v_cvt_pk_bf16_f32 v0, v12, v13
	v_cvt_pk_bf16_f32 v1, v14, v15
	v_cvt_pk_bf16_f32 v2, v8, v9
	v_cvt_pk_bf16_f32 v3, v10, v11
	s_mov_b64 s[0:1], -1
	v_cvt_pk_bf16_f32 v4, v4, v5
	v_cvt_pk_bf16_f32 v5, v6, v7
	v_cvt_pk_bf16_f32 v6, v20, v21
	v_cvt_pk_bf16_f32 v7, v22, v23
	global_store_dwordx4 v[18:19], v[0:3], off
	global_store_dwordx4 v[16:17], v[4:7], off offset:256
	s_mov_b64 s[96:97], vcc
	s_cmp_lt_i32 s5, 8
	s_cbranch_scc1 .Lkn_skip
	s_cmp_gt_i32 s5, 15
	s_cbranch_scc1 .Lkn_skip
	s_waitcnt vmcnt(0)
	s_barrier
	v_and_b32_e32 v0, 0xff, v255
	s_lshl_b32 s89, s4, 8
	v_add_u32_e32 v0, s89, v0
	v_lshlrev_b32_e32 v0, 14, v0
	v_lshrrev_b32_e32 v1, 8, v255
	v_lshlrev_b32_e32 v1, 8, v1
	s_lshl_b32 s89, s5, 9
	v_add3_u32 v0, v0, v1, s89
	global_load_dwordx4 v[2:5], v0, s[10:11] sc1
	global_load_dwordx4 v[6:9], v0, s[10:11] offset:16 sc1
	global_load_dwordx4 v[10:13], v0, s[10:11] offset:32 sc1
	global_load_dwordx4 v[14:17], v0, s[10:11] offset:48 sc1
	global_load_dwordx4 v[18:21], v0, s[10:11] offset:64 sc1
	global_load_dwordx4 v[22:25], v0, s[10:11] offset:80 sc1
	global_load_dwordx4 v[26:29], v0, s[10:11] offset:96 sc1
	global_load_dwordx4 v[30:33], v0, s[10:11] offset:112 sc1
	global_load_dwordx4 v[34:37], v0, s[10:11] offset:128 sc1
	global_load_dwordx4 v[38:41], v0, s[10:11] offset:144 sc1
	global_load_dwordx4 v[42:45], v0, s[10:11] offset:160 sc1
	global_load_dwordx4 v[46:49], v0, s[10:11] offset:176 sc1
	global_load_dwordx4 v[50:53], v0, s[10:11] offset:192 sc1
	global_load_dwordx4 v[54:57], v0, s[10:11] offset:208 sc1
	global_load_dwordx4 v[58:61], v0, s[10:11] offset:224 sc1
	global_load_dwordx4 v[62:65], v0, s[10:11] offset:240 sc1
	s_waitcnt vmcnt(15)
	v_lshlrev_b32_e32 v67, 16, v2
	v_and_b32_e32 v68, 0xffff0000, v2
	v_mul_f32_e32 v66, v67, v67
	v_fmac_f32_e32 v66, v68, v68
	v_lshlrev_b32_e32 v67, 16, v3
	v_and_b32_e32 v68, 0xffff0000, v3
	v_fmac_f32_e32 v66, v67, v67
	v_fmac_f32_e32 v66, v68, v68
	v_lshlrev_b32_e32 v67, 16, v4
	v_and_b32_e32 v68, 0xffff0000, v4
	v_fmac_f32_e32 v66, v67, v67
	v_fmac_f32_e32 v66, v68, v68
	v_lshlrev_b32_e32 v67, 16, v5
	v_and_b32_e32 v68, 0xffff0000, v5
	v_fmac_f32_e32 v66, v67, v67
	v_fmac_f32_e32 v66, v68, v68
	s_waitcnt vmcnt(14)
	v_lshlrev_b32_e32 v67, 16, v6
	v_and_b32_e32 v68, 0xffff0000, v6
	v_fmac_f32_e32 v66, v67, v67
	v_fmac_f32_e32 v66, v68, v68
	v_lshlrev_b32_e32 v67, 16, v7
	v_and_b32_e32 v68, 0xffff0000, v7
	v_fmac_f32_e32 v66, v67, v67
	v_fmac_f32_e32 v66, v68, v68
	v_lshlrev_b32_e32 v67, 16, v8
	v_and_b32_e32 v68, 0xffff0000, v8
	v_fmac_f32_e32 v66, v67, v67
	v_fmac_f32_e32 v66, v68, v68
	v_lshlrev_b32_e32 v67, 16, v9
	v_and_b32_e32 v68, 0xffff0000, v9
	v_fmac_f32_e32 v66, v67, v67
	v_fmac_f32_e32 v66, v68, v68
	s_waitcnt vmcnt(13)
	v_lshlrev_b32_e32 v67, 16, v10
	v_and_b32_e32 v68, 0xffff0000, v10
	v_fmac_f32_e32 v66, v67, v67
	v_fmac_f32_e32 v66, v68, v68
	v_lshlrev_b32_e32 v67, 16, v11
	v_and_b32_e32 v68, 0xffff0000, v11
	v_fmac_f32_e32 v66, v67, v67
	v_fmac_f32_e32 v66, v68, v68
	v_lshlrev_b32_e32 v67, 16, v12
	v_and_b32_e32 v68, 0xffff0000, v12
	v_fmac_f32_e32 v66, v67, v67
	v_fmac_f32_e32 v66, v68, v68
	v_lshlrev_b32_e32 v67, 16, v13
	v_and_b32_e32 v68, 0xffff0000, v13
	v_fmac_f32_e32 v66, v67, v67
	v_fmac_f32_e32 v66, v68, v68
	s_waitcnt vmcnt(12)
	v_lshlrev_b32_e32 v67, 16, v14
	v_and_b32_e32 v68, 0xffff0000, v14
	v_fmac_f32_e32 v66, v67, v67
	v_fmac_f32_e32 v66, v68, v68
	v_lshlrev_b32_e32 v67, 16, v15
	v_and_b32_e32 v68, 0xffff0000, v15
	v_fmac_f32_e32 v66, v67, v67
	v_fmac_f32_e32 v66, v68, v68
	v_lshlrev_b32_e32 v67, 16, v16
	v_and_b32_e32 v68, 0xffff0000, v16
	v_fmac_f32_e32 v66, v67, v67
	v_fmac_f32_e32 v66, v68, v68
	v_lshlrev_b32_e32 v67, 16, v17
	v_and_b32_e32 v68, 0xffff0000, v17
	v_fmac_f32_e32 v66, v67, v67
	v_fmac_f32_e32 v66, v68, v68
	s_waitcnt vmcnt(11)
	v_lshlrev_b32_e32 v67, 16, v18
	v_and_b32_e32 v68, 0xffff0000, v18
	v_fmac_f32_e32 v66, v67, v67
	v_fmac_f32_e32 v66, v68, v68
	v_lshlrev_b32_e32 v67, 16, v19
	v_and_b32_e32 v68, 0xffff0000, v19
	v_fmac_f32_e32 v66, v67, v67
	v_fmac_f32_e32 v66, v68, v68
	v_lshlrev_b32_e32 v67, 16, v20
	v_and_b32_e32 v68, 0xffff0000, v20
	v_fmac_f32_e32 v66, v67, v67
	v_fmac_f32_e32 v66, v68, v68
	v_lshlrev_b32_e32 v67, 16, v21
	v_and_b32_e32 v68, 0xffff0000, v21
	v_fmac_f32_e32 v66, v67, v67
	v_fmac_f32_e32 v66, v68, v68
	s_waitcnt vmcnt(10)
	v_lshlrev_b32_e32 v67, 16, v22
	v_and_b32_e32 v68, 0xffff0000, v22
	v_fmac_f32_e32 v66, v67, v67
	v_fmac_f32_e32 v66, v68, v68
	v_lshlrev_b32_e32 v67, 16, v23
	v_and_b32_e32 v68, 0xffff0000, v23
	v_fmac_f32_e32 v66, v67, v67
	v_fmac_f32_e32 v66, v68, v68
	v_lshlrev_b32_e32 v67, 16, v24
	v_and_b32_e32 v68, 0xffff0000, v24
	v_fmac_f32_e32 v66, v67, v67
	v_fmac_f32_e32 v66, v68, v68
	v_lshlrev_b32_e32 v67, 16, v25
	v_and_b32_e32 v68, 0xffff0000, v25
	v_fmac_f32_e32 v66, v67, v67
	v_fmac_f32_e32 v66, v68, v68
	s_waitcnt vmcnt(9)
	v_lshlrev_b32_e32 v67, 16, v26
	v_and_b32_e32 v68, 0xffff0000, v26
	v_fmac_f32_e32 v66, v67, v67
	v_fmac_f32_e32 v66, v68, v68
	v_lshlrev_b32_e32 v67, 16, v27
	v_and_b32_e32 v68, 0xffff0000, v27
	v_fmac_f32_e32 v66, v67, v67
	v_fmac_f32_e32 v66, v68, v68
	v_lshlrev_b32_e32 v67, 16, v28
	v_and_b32_e32 v68, 0xffff0000, v28
	v_fmac_f32_e32 v66, v67, v67
	v_fmac_f32_e32 v66, v68, v68
	v_lshlrev_b32_e32 v67, 16, v29
	v_and_b32_e32 v68, 0xffff0000, v29
	v_fmac_f32_e32 v66, v67, v67
	v_fmac_f32_e32 v66, v68, v68
	s_waitcnt vmcnt(8)
	v_lshlrev_b32_e32 v67, 16, v30
	v_and_b32_e32 v68, 0xffff0000, v30
	v_fmac_f32_e32 v66, v67, v67
	v_fmac_f32_e32 v66, v68, v68
	v_lshlrev_b32_e32 v67, 16, v31
	v_and_b32_e32 v68, 0xffff0000, v31
	v_fmac_f32_e32 v66, v67, v67
	v_fmac_f32_e32 v66, v68, v68
	v_lshlrev_b32_e32 v67, 16, v32
	v_and_b32_e32 v68, 0xffff0000, v32
	v_fmac_f32_e32 v66, v67, v67
	v_fmac_f32_e32 v66, v68, v68
	v_lshlrev_b32_e32 v67, 16, v33
	v_and_b32_e32 v68, 0xffff0000, v33
	v_fmac_f32_e32 v66, v67, v67
	v_fmac_f32_e32 v66, v68, v68
	s_waitcnt vmcnt(7)
	v_lshlrev_b32_e32 v67, 16, v34
	v_and_b32_e32 v68, 0xffff0000, v34
	v_fmac_f32_e32 v66, v67, v67
	v_fmac_f32_e32 v66, v68, v68
	v_lshlrev_b32_e32 v67, 16, v35
	v_and_b32_e32 v68, 0xffff0000, v35
	v_fmac_f32_e32 v66, v67, v67
	v_fmac_f32_e32 v66, v68, v68
	v_lshlrev_b32_e32 v67, 16, v36
	v_and_b32_e32 v68, 0xffff0000, v36
	v_fmac_f32_e32 v66, v67, v67
	v_fmac_f32_e32 v66, v68, v68
	v_lshlrev_b32_e32 v67, 16, v37
	v_and_b32_e32 v68, 0xffff0000, v37
	v_fmac_f32_e32 v66, v67, v67
	v_fmac_f32_e32 v66, v68, v68
	s_waitcnt vmcnt(6)
	v_lshlrev_b32_e32 v67, 16, v38
	v_and_b32_e32 v68, 0xffff0000, v38
	v_fmac_f32_e32 v66, v67, v67
	v_fmac_f32_e32 v66, v68, v68
	v_lshlrev_b32_e32 v67, 16, v39
	v_and_b32_e32 v68, 0xffff0000, v39
	v_fmac_f32_e32 v66, v67, v67
	v_fmac_f32_e32 v66, v68, v68
	v_lshlrev_b32_e32 v67, 16, v40
	v_and_b32_e32 v68, 0xffff0000, v40
	v_fmac_f32_e32 v66, v67, v67
	v_fmac_f32_e32 v66, v68, v68
	v_lshlrev_b32_e32 v67, 16, v41
	v_and_b32_e32 v68, 0xffff0000, v41
	v_fmac_f32_e32 v66, v67, v67
	v_fmac_f32_e32 v66, v68, v68
	s_waitcnt vmcnt(5)
	v_lshlrev_b32_e32 v67, 16, v42
	v_and_b32_e32 v68, 0xffff0000, v42
	v_fmac_f32_e32 v66, v67, v67
	v_fmac_f32_e32 v66, v68, v68
	v_lshlrev_b32_e32 v67, 16, v43
	v_and_b32_e32 v68, 0xffff0000, v43
	v_fmac_f32_e32 v66, v67, v67
	v_fmac_f32_e32 v66, v68, v68
	v_lshlrev_b32_e32 v67, 16, v44
	v_and_b32_e32 v68, 0xffff0000, v44
	v_fmac_f32_e32 v66, v67, v67
	v_fmac_f32_e32 v66, v68, v68
	v_lshlrev_b32_e32 v67, 16, v45
	v_and_b32_e32 v68, 0xffff0000, v45
	v_fmac_f32_e32 v66, v67, v67
	v_fmac_f32_e32 v66, v68, v68
	s_waitcnt vmcnt(4)
	v_lshlrev_b32_e32 v67, 16, v46
	v_and_b32_e32 v68, 0xffff0000, v46
	v_fmac_f32_e32 v66, v67, v67
	v_fmac_f32_e32 v66, v68, v68
	v_lshlrev_b32_e32 v67, 16, v47
	v_and_b32_e32 v68, 0xffff0000, v47
	v_fmac_f32_e32 v66, v67, v67
	v_fmac_f32_e32 v66, v68, v68
	v_lshlrev_b32_e32 v67, 16, v48
	v_and_b32_e32 v68, 0xffff0000, v48
	v_fmac_f32_e32 v66, v67, v67
	v_fmac_f32_e32 v66, v68, v68
	v_lshlrev_b32_e32 v67, 16, v49
	v_and_b32_e32 v68, 0xffff0000, v49
	v_fmac_f32_e32 v66, v67, v67
	v_fmac_f32_e32 v66, v68, v68
	s_waitcnt vmcnt(3)
	v_lshlrev_b32_e32 v67, 16, v50
	v_and_b32_e32 v68, 0xffff0000, v50
	v_fmac_f32_e32 v66, v67, v67
	v_fmac_f32_e32 v66, v68, v68
	v_lshlrev_b32_e32 v67, 16, v51
	v_and_b32_e32 v68, 0xffff0000, v51
	v_fmac_f32_e32 v66, v67, v67
	v_fmac_f32_e32 v66, v68, v68
	v_lshlrev_b32_e32 v67, 16, v52
	v_and_b32_e32 v68, 0xffff0000, v52
	v_fmac_f32_e32 v66, v67, v67
	v_fmac_f32_e32 v66, v68, v68
	v_lshlrev_b32_e32 v67, 16, v53
	v_and_b32_e32 v68, 0xffff0000, v53
	v_fmac_f32_e32 v66, v67, v67
	v_fmac_f32_e32 v66, v68, v68
	s_waitcnt vmcnt(2)
	v_lshlrev_b32_e32 v67, 16, v54
	v_and_b32_e32 v68, 0xffff0000, v54
	v_fmac_f32_e32 v66, v67, v67
	v_fmac_f32_e32 v66, v68, v68
	v_lshlrev_b32_e32 v67, 16, v55
	v_and_b32_e32 v68, 0xffff0000, v55
	v_fmac_f32_e32 v66, v67, v67
	v_fmac_f32_e32 v66, v68, v68
	v_lshlrev_b32_e32 v67, 16, v56
	v_and_b32_e32 v68, 0xffff0000, v56
	v_fmac_f32_e32 v66, v67, v67
	v_fmac_f32_e32 v66, v68, v68
	v_lshlrev_b32_e32 v67, 16, v57
	v_and_b32_e32 v68, 0xffff0000, v57
	v_fmac_f32_e32 v66, v67, v67
	v_fmac_f32_e32 v66, v68, v68
	s_waitcnt vmcnt(1)
	v_lshlrev_b32_e32 v67, 16, v58
	v_and_b32_e32 v68, 0xffff0000, v58
	v_fmac_f32_e32 v66, v67, v67
	v_fmac_f32_e32 v66, v68, v68
	v_lshlrev_b32_e32 v67, 16, v59
	v_and_b32_e32 v68, 0xffff0000, v59
	v_fmac_f32_e32 v66, v67, v67
	v_fmac_f32_e32 v66, v68, v68
	v_lshlrev_b32_e32 v67, 16, v60
	v_and_b32_e32 v68, 0xffff0000, v60
	v_fmac_f32_e32 v66, v67, v67
	v_fmac_f32_e32 v66, v68, v68
	v_lshlrev_b32_e32 v67, 16, v61
	v_and_b32_e32 v68, 0xffff0000, v61
	v_fmac_f32_e32 v66, v67, v67
	v_fmac_f32_e32 v66, v68, v68
	s_waitcnt vmcnt(0)
	v_lshlrev_b32_e32 v67, 16, v62
	v_and_b32_e32 v68, 0xffff0000, v62
	v_fmac_f32_e32 v66, v67, v67
	v_fmac_f32_e32 v66, v68, v68
	v_lshlrev_b32_e32 v67, 16, v63
	v_and_b32_e32 v68, 0xffff0000, v63
	v_fmac_f32_e32 v66, v67, v67
	v_fmac_f32_e32 v66, v68, v68
	v_lshlrev_b32_e32 v67, 16, v64
	v_and_b32_e32 v68, 0xffff0000, v64
	v_fmac_f32_e32 v66, v67, v67
	v_fmac_f32_e32 v66, v68, v68
	v_lshlrev_b32_e32 v67, 16, v65
	v_and_b32_e32 v68, 0xffff0000, v65
	v_fmac_f32_e32 v66, v67, v67
	v_fmac_f32_e32 v66, v68, v68
	s_nop 1
	v_max_f32_dpp v66, v66, v66 row_ror:8 row_mask:0xf bank_mask:0xf
	s_nop 1
	v_max_f32_dpp v66, v66, v66 row_ror:4 row_mask:0xf bank_mask:0xf
	s_nop 1
	v_max_f32_dpp v66, v66, v66 row_ror:2 row_mask:0xf bank_mask:0xf
	s_nop 1
	v_max_f32_dpp v66, v66, v66 row_ror:1 row_mask:0xf bank_mask:0xf
	s_nop 1
	v_readlane_b32 s89, v66, 0
	v_readlane_b32 s90, v66, 16
	v_readlane_b32 s91, v66, 32
	v_readlane_b32 s92, v66, 48
	s_max_u32 s89, s89, s90
	s_max_u32 s91, s91, s92
	s_max_u32 s89, s89, s91
	v_readfirstlane_b32 s90, v255
	s_lshr_b32 s90, s90, 8
	s_sub_i32 s91, s5, 8
	s_lshl_b32 s91, s91, 1
	s_add_i32 s91, s91, s90
	s_lshr_b32 s92, s4, 4
	s_lshl_b32 s92, s92, 4
	s_add_i32 s91, s91, s92
	s_lshl_b32 s91, s91, 2
	s_addk_i32 s91, 640
	s_add_u32 s92, s54, 0x80000
	s_addc_u32 s93, s55, 0
	s_mov_b64 s[94:95], exec
	s_mov_b64 exec, 1
	v_mov_b32_e32 v0, s91
	v_mov_b32_e32 v1, s89
	global_atomic_umax v0, v1, s[92:93]
	s_mov_b64 exec, s[94:95]
.Lkn_skip:
	s_mov_b64 vcc, s[96:97]
	s_cbranch_vccnz .LBB0_553
	s_andn2_b64 vcc, exec, s[6:7]
	s_cbranch_vccnz .LBB0_552
	s_barrier
	s_branch .LBB0_552
